# diff and MLA softmax sections rewritten by hand (max3 tree, batched sub/exp, packed partial sums), same structure as the DSA one
# speedup vs baseline: 1.0119x; 1.0070x over previous
; __device__ __forceinline__ unsigned cvtpk(float lo, float hi) { unsigned r; asm("v_cvt_pk_bf16_f32 %0, %1, %2" : "=v"(r) : "v"(lo), "v"(hi)); return r; }
; __device__ __forceinline__ float max_x32(float v) { const unsigned u = __float_as_uint(v); auto r = __builtin_amdgcn_permlane32_swap(u, u, false, false); return fmaxf(__uint_as_float(r[0]), __uint_as_float(r[1])); }
; template <bool MASKED>
; __device__ __forceinline__ void softmax_tile(f32x16& s0, f32x16& s1, float& m, float& l, float& alpha, unsigned mlo, unsigned mhi, bf16x8 (&pk)[4]) {
;     ...
;     float mx = fmaxf(s0[0], s1[0]);
; #pragma unroll
;     for (int r = 1; r < 16; ++r) mx = fmaxf(mx, fmaxf(s0[r], s1[r]));
;     mx = max_x32(mx);
;     const float mn = fmaxf(m, mx);
;     alpha = __builtin_amdgcn_exp2f(m - mn); m = mn;
;     float sum = 0.f;
; #pragma unroll
;     for (int r = 0; r < 16; ++r) {
;         float p0 = __builtin_amdgcn_exp2f(s0[r] - mn), p1 = __builtin_amdgcn_exp2f(s1[r] - mn);
;         if (MASKED) { if (s0[r] <= -1e29f) p0 = 0.f; if (s1[r] <= -1e29f) p1 = 0.f; }
;         s0[r] = p0; s1[r] = p1; sum += p0 + p1;
;     }
;     l = l * alpha + sum;
; #pragma unroll
;     for (int k2 = 0; k2 < 2; ++k2) {
;         u32x4 a, b;
;         a.x = cvtpk(s0[8 * k2 + 0], s0[8 * k2 + 1]); a.y = cvtpk(s0[8 * k2 + 2], s0[8 * k2 + 3]); a.z = cvtpk(s0[8 * k2 + 4], s0[8 * k2 + 5]); a.w = cvtpk(s0[8 * k2 + 6], s0[8 * k2 + 7]);
;         b.x = cvtpk(s1[8 * k2 + 0], s1[8 * k2 + 1]); b.y = cvtpk(s1[8 * k2 + 2], s1[8 * k2 + 3]); b.z = cvtpk(s1[8 * k2 + 4], s1[8 * k2 + 5]); b.w = cvtpk(s1[8 * k2 + 6], s1[8 * k2 + 7]);
;         pk[k2] = __builtin_bit_cast(bf16x8, a); pk[2 + k2] = __builtin_bit_cast(bf16x8, b);
;     }
; }
.LBB0_626:
	s_cmp_gt_i32 s7, s25
	s_cbranch_scc1 .LBB0_630
	s_mul_i32 s26, s17, 0xa000
	s_add_i32 s26, s26, 0
	v_add_u32_e32 v0, s26, v124
	v_add_u32_e32 v70, v0, v126
	v_add_u32_e32 v74, v0, v127
	ds_read_b128 v[66:69], v70
	ds_read_b128 v[70:73], v70 offset:8192
	ds_read_b128 v[150:153], v74
	ds_read_b128 v[154:157], v74 offset:8192
	v_add_u32_e32 v74, v0, v128
	v_add_u32_e32 v0, v0, v129
	ds_read_b128 v[158:161], v74
	ds_read_b128 v[162:165], v74 offset:8192
	ds_read_b128 v[166:169], v0
	ds_read_b128 v[170:173], v0 offset:8192
	s_waitcnt lgkmcnt(0)
	v_mfma_f32_32x32x16_bf16 v[82:97], v[66:69], v[98:101], 0
	v_mfma_f32_32x32x16_bf16 v[66:81], v[70:73], v[98:101], 0
	v_mfma_f32_32x32x16_bf16 v[82:97], v[150:153], v[102:105], v[82:97]
	v_mfma_f32_32x32x16_bf16 v[66:81], v[154:157], v[102:105], v[66:81]
	v_mfma_f32_32x32x16_bf16 v[82:97], v[158:161], v[106:109], v[82:97]
	v_mfma_f32_32x32x16_bf16 v[66:81], v[162:165], v[106:109], v[66:81]
	v_mfma_f32_32x32x16_bf16 v[82:97], v[166:169], v[110:113], v[82:97]
	v_mfma_f32_32x32x16_bf16 v[66:81], v[170:173], v[110:113], v[66:81]
	s_nop 11
	v_max3_f32 v150, v82, v83, v84
	v_max3_f32 v151, v85, v86, v87
	v_max3_f32 v152, v88, v89, v90
	v_max3_f32 v153, v91, v92, v93
	v_max3_f32 v154, v94, v95, v96
	v_max3_f32 v155, v97, v66, v67
	v_max3_f32 v156, v68, v69, v70
	v_max3_f32 v157, v71, v72, v73
	v_max3_f32 v158, v74, v75, v76
	v_max3_f32 v159, v77, v78, v79
	v_max3_f32 v150, v150, v151, v152
	v_max3_f32 v153, v153, v154, v155
	v_max3_f32 v156, v156, v157, v158
	v_max3_f32 v159, v159, v80, v81
	v_max3_f32 v150, v150, v153, v156
	v_max_f32_e32 v150, v150, v159
	v_mov_b32_e32 v151, v150
	s_nop 1
	v_permlane32_swap_b32_e32 v150, v151
	v_max3_f32 v146, v148, v150, v151
	v_sub_f32_e32 v0, v148, v146
	v_sub_f32_e32 v82, v82, v146
	v_sub_f32_e32 v83, v83, v146
	v_sub_f32_e32 v84, v84, v146
	v_sub_f32_e32 v85, v85, v146
	v_sub_f32_e32 v86, v86, v146
	v_sub_f32_e32 v87, v87, v146
	v_sub_f32_e32 v88, v88, v146
	v_sub_f32_e32 v89, v89, v146
	v_sub_f32_e32 v90, v90, v146
	v_sub_f32_e32 v91, v91, v146
	v_sub_f32_e32 v92, v92, v146
	v_sub_f32_e32 v93, v93, v146
	v_sub_f32_e32 v94, v94, v146
	v_sub_f32_e32 v95, v95, v146
	v_sub_f32_e32 v96, v96, v146
	v_sub_f32_e32 v97, v97, v146
	v_sub_f32_e32 v66, v66, v146
	v_sub_f32_e32 v67, v67, v146
	v_sub_f32_e32 v68, v68, v146
	v_sub_f32_e32 v69, v69, v146
	v_sub_f32_e32 v70, v70, v146
	v_sub_f32_e32 v71, v71, v146
	v_sub_f32_e32 v72, v72, v146
	v_sub_f32_e32 v73, v73, v146
	v_sub_f32_e32 v74, v74, v146
	v_sub_f32_e32 v75, v75, v146
	v_sub_f32_e32 v76, v76, v146
	v_sub_f32_e32 v77, v77, v146
	v_sub_f32_e32 v78, v78, v146
	v_sub_f32_e32 v79, v79, v146
	v_sub_f32_e32 v80, v80, v146
	v_sub_f32_e32 v81, v81, v146
	v_exp_f32_e32 v0, v0
	v_exp_f32_e32 v82, v82
	v_exp_f32_e32 v83, v83
	v_exp_f32_e32 v84, v84
	v_exp_f32_e32 v85, v85
	v_exp_f32_e32 v86, v86
	v_exp_f32_e32 v87, v87
	v_exp_f32_e32 v88, v88
	v_exp_f32_e32 v89, v89
	v_exp_f32_e32 v90, v90
	v_exp_f32_e32 v91, v91
	v_exp_f32_e32 v92, v92
	v_exp_f32_e32 v93, v93
	v_exp_f32_e32 v94, v94
	v_exp_f32_e32 v95, v95
	v_exp_f32_e32 v96, v96
	v_exp_f32_e32 v97, v97
	v_exp_f32_e32 v66, v66
	v_exp_f32_e32 v67, v67
	v_exp_f32_e32 v68, v68
	v_exp_f32_e32 v69, v69
	v_exp_f32_e32 v70, v70
	v_exp_f32_e32 v71, v71
	v_exp_f32_e32 v72, v72
	v_exp_f32_e32 v73, v73
	v_exp_f32_e32 v74, v74
	v_exp_f32_e32 v75, v75
	v_exp_f32_e32 v76, v76
	v_exp_f32_e32 v77, v77
	v_exp_f32_e32 v78, v78
	v_exp_f32_e32 v79, v79
	v_exp_f32_e32 v80, v80
	v_exp_f32_e32 v81, v81
	v_pk_add_f32 v[150:151], v[82:83], v[84:85]
	v_pk_add_f32 v[152:153], v[86:87], v[88:89]
	v_pk_add_f32 v[154:155], v[90:91], v[92:93]
	v_pk_add_f32 v[156:157], v[94:95], v[96:97]
	v_pk_add_f32 v[158:159], v[66:67], v[68:69]
	v_pk_add_f32 v[160:161], v[70:71], v[72:73]
	v_pk_add_f32 v[162:163], v[74:75], v[76:77]
	v_pk_add_f32 v[164:165], v[78:79], v[80:81]
	v_pk_add_f32 v[150:151], v[150:151], v[152:153]
	v_pk_add_f32 v[154:155], v[154:155], v[156:157]
	v_pk_add_f32 v[158:159], v[158:159], v[160:161]
	v_pk_add_f32 v[162:163], v[162:163], v[164:165]
	v_pk_add_f32 v[150:151], v[150:151], v[154:155]
	v_pk_add_f32 v[158:159], v[158:159], v[162:163]
	v_pk_add_f32 v[150:151], v[150:151], v[158:159]
	v_add_f32_e32 v164, v150, v151
	v_cvt_pk_bf16_f32 v66, v66, v67
	v_cvt_pk_bf16_f32 v67, v68, v69
	v_cvt_pk_bf16_f32 v68, v70, v71
	v_cvt_pk_bf16_f32 v69, v72, v73
	v_cvt_pk_bf16_f32 v70, v74, v75
	v_cvt_pk_bf16_f32 v71, v76, v77
	v_cvt_pk_bf16_f32 v72, v78, v79
	v_cvt_pk_bf16_f32 v73, v80, v81
	v_cvt_pk_bf16_f32 v74, v82, v83
	v_cvt_pk_bf16_f32 v75, v84, v85
	v_cvt_pk_bf16_f32 v76, v86, v87
	v_cvt_pk_bf16_f32 v77, v88, v89
	v_cvt_pk_bf16_f32 v78, v90, v91
	v_cvt_pk_bf16_f32 v79, v92, v93
	v_cvt_pk_bf16_f32 v80, v94, v95
	v_cvt_pk_bf16_f32 v81, v96, v97
	v_fmac_f32_e32 v164, v147, v0
	v_cmp_neq_f32_e32 vcc, 1.0, v0
	s_cbranch_vccz .LBB0_629
	v_pk_mul_f32 v[64:65], v[64:65], v[0:1] op_sel_hi:[1,0]
	v_pk_mul_f32 v[62:63], v[62:63], v[0:1] op_sel_hi:[1,0]
	v_pk_mul_f32 v[60:61], v[60:61], v[0:1] op_sel_hi:[1,0]
	v_pk_mul_f32 v[58:59], v[58:59], v[0:1] op_sel_hi:[1,0]
	v_pk_mul_f32 v[56:57], v[56:57], v[0:1] op_sel_hi:[1,0]
	v_pk_mul_f32 v[54:55], v[54:55], v[0:1] op_sel_hi:[1,0]
	v_pk_mul_f32 v[52:53], v[52:53], v[0:1] op_sel_hi:[1,0]
	v_pk_mul_f32 v[50:51], v[50:51], v[0:1] op_sel_hi:[1,0]
	v_pk_mul_f32 v[48:49], v[48:49], v[0:1] op_sel_hi:[1,0]
	v_pk_mul_f32 v[46:47], v[46:47], v[0:1] op_sel_hi:[1,0]
	v_pk_mul_f32 v[44:45], v[44:45], v[0:1] op_sel_hi:[1,0]
	v_pk_mul_f32 v[42:43], v[42:43], v[0:1] op_sel_hi:[1,0]
	v_pk_mul_f32 v[40:41], v[40:41], v[0:1] op_sel_hi:[1,0]
	v_pk_mul_f32 v[38:39], v[38:39], v[0:1] op_sel_hi:[1,0]
	v_pk_mul_f32 v[36:37], v[36:37], v[0:1] op_sel_hi:[1,0]
	v_pk_mul_f32 v[34:35], v[34:35], v[0:1] op_sel_hi:[1,0]
	v_pk_mul_f32 v[32:33], v[32:33], v[0:1] op_sel_hi:[1,0]
	v_pk_mul_f32 v[30:31], v[30:31], v[0:1] op_sel_hi:[1,0]
	v_pk_mul_f32 v[28:29], v[28:29], v[0:1] op_sel_hi:[1,0]
	v_pk_mul_f32 v[26:27], v[26:27], v[0:1] op_sel_hi:[1,0]
	v_pk_mul_f32 v[24:25], v[24:25], v[0:1] op_sel_hi:[1,0]
	v_pk_mul_f32 v[22:23], v[22:23], v[0:1] op_sel_hi:[1,0]
	v_pk_mul_f32 v[20:21], v[20:21], v[0:1] op_sel_hi:[1,0]
	v_pk_mul_f32 v[18:19], v[18:19], v[0:1] op_sel_hi:[1,0]
	v_pk_mul_f32 v[16:17], v[16:17], v[0:1] op_sel_hi:[1,0]
	v_pk_mul_f32 v[14:15], v[14:15], v[0:1] op_sel_hi:[1,0]
	v_pk_mul_f32 v[12:13], v[12:13], v[0:1] op_sel_hi:[1,0]
	v_pk_mul_f32 v[10:11], v[10:11], v[0:1] op_sel_hi:[1,0]
	v_pk_mul_f32 v[8:9], v[8:9], v[0:1] op_sel_hi:[1,0]
	v_pk_mul_f32 v[6:7], v[6:7], v[0:1] op_sel_hi:[1,0]
	v_pk_mul_f32 v[4:5], v[4:5], v[0:1] op_sel_hi:[1,0]
	v_pk_mul_f32 v[2:3], v[2:3], v[0:1] op_sel_hi:[1,0]

; __device__ __forceinline__ unsigned cvtpk(float lo, float hi) { unsigned r; asm("v_cvt_pk_bf16_f32 %0, %1, %2" : "=v"(r) : "v"(lo), "v"(hi)); return r; }
; __device__ __forceinline__ float max_x32(float v) { const unsigned u = __float_as_uint(v); auto r = __builtin_amdgcn_permlane32_swap(u, u, false, false); return fmaxf(__uint_as_float(r[0]), __uint_as_float(r[1])); }
; template <bool MASKED>
; __device__ __forceinline__ void softmax_tile(f32x16& s0, f32x16& s1, float& m, float& l, float& alpha, unsigned mlo, unsigned mhi, bf16x8 (&pk)[4]) {
;     ...
;     float mx = fmaxf(s0[0], s1[0]);
; #pragma unroll
;     for (int r = 1; r < 16; ++r) mx = fmaxf(mx, fmaxf(s0[r], s1[r]));
;     mx = max_x32(mx);
;     const float mn = fmaxf(m, mx);
;     alpha = __builtin_amdgcn_exp2f(m - mn); m = mn;
;     float sum = 0.f;
; #pragma unroll
;     for (int r = 0; r < 16; ++r) {
;         float p0 = __builtin_amdgcn_exp2f(s0[r] - mn), p1 = __builtin_amdgcn_exp2f(s1[r] - mn);
;         if (MASKED) { if (s0[r] <= -1e29f) p0 = 0.f; if (s1[r] <= -1e29f) p1 = 0.f; }
;         s0[r] = p0; s1[r] = p1; sum += p0 + p1;
;     }
;     l = l * alpha + sum;
; #pragma unroll
;     for (int k2 = 0; k2 < 2; ++k2) {
;         u32x4 a, b;
;         a.x = cvtpk(s0[8 * k2 + 0], s0[8 * k2 + 1]); a.y = cvtpk(s0[8 * k2 + 2], s0[8 * k2 + 3]); a.z = cvtpk(s0[8 * k2 + 4], s0[8 * k2 + 5]); a.w = cvtpk(s0[8 * k2 + 6], s0[8 * k2 + 7]);
;         b.x = cvtpk(s1[8 * k2 + 0], s1[8 * k2 + 1]); b.y = cvtpk(s1[8 * k2 + 2], s1[8 * k2 + 3]); b.z = cvtpk(s1[8 * k2 + 4], s1[8 * k2 + 5]); b.w = cvtpk(s1[8 * k2 + 6], s1[8 * k2 + 7]);
;         pk[k2] = __builtin_bit_cast(bf16x8, a); pk[2 + k2] = __builtin_bit_cast(bf16x8, b);
;     }
; }
.LBB0_1190:
	s_cmp_gt_i32 s14, s49
	s_cbranch_scc1 .LBB0_1194
	s_mul_i32 s15, s50, 0xa000
	s_add_i32 s15, s15, 0
	v_add_u32_e32 v0, s15, v186
	v_add_u32_e32 v6, v0, v188
	v_add_u32_e32 v14, v0, v189
	ds_read_b128 v[2:5], v6
	ds_read_b128 v[6:9], v6 offset:8192
	ds_read_b128 v[10:13], v14
	ds_read_b128 v[160:163], v14 offset:8192
	v_add_u32_e32 v14, v0, v190
	ds_read_b128 v[164:167], v14
	ds_read_b128 v[168:171], v14 offset:8192
	v_add_u32_e32 v14, v0, v191
	ds_read_b128 v[172:175], v14 offset:8192
	ds_read_b128 v[206:209], v14
	v_add_u32_e32 v14, s15, v177
	s_waitcnt lgkmcnt(0)
	v_mfma_f32_32x32x16_bf16 v[96:111], v[2:5], v[112:115], 0
	v_mfma_f32_32x32x16_bf16 v[80:95], v[6:9], v[112:115], 0
	v_mfma_f32_32x32x16_bf16 v[96:111], v[10:13], v[116:119], v[96:111]
	v_mfma_f32_32x32x16_bf16 v[80:95], v[160:163], v[116:119], v[80:95]
	v_mfma_f32_32x32x16_bf16 v[96:111], v[164:167], v[120:123], v[96:111]
	v_mfma_f32_32x32x16_bf16 v[80:95], v[168:171], v[120:123], v[80:95]
	v_mfma_f32_32x32x16_bf16 v[96:111], v[206:209], v[124:127], v[96:111]
	v_mfma_f32_32x32x16_bf16 v[80:95], v[172:175], v[124:127], v[80:95]
	v_add_u32_e32 v6, v0, v192
	v_add_u32_e32 v15, v0, v193
	ds_read_b128 v[2:5], v6
	ds_read_b128 v[6:9], v6 offset:8192
	ds_read_b128 v[10:13], v15
	ds_read_b128 v[160:163], v15 offset:8192
	v_add_u32_e32 v15, v0, v194
	v_add_u32_e32 v0, v0, v195
	ds_read_b128 v[164:167], v15
	ds_read_b128 v[168:171], v15 offset:8192
	ds_read_b128 v[172:175], v0 offset:8192
	ds_read_b128 v[206:209], v0
	s_waitcnt lgkmcnt(0)
	v_mfma_f32_32x32x16_bf16 v[96:111], v[2:5], v[128:131], v[96:111]
	v_mfma_f32_32x32x16_bf16 v[80:95], v[6:9], v[128:131], v[80:95]
	v_mfma_f32_32x32x16_bf16 v[96:111], v[10:13], v[132:135], v[96:111]
	v_mfma_f32_32x32x16_bf16 v[80:95], v[160:163], v[132:135], v[80:95]
	v_mfma_f32_32x32x16_bf16 v[96:111], v[164:167], v[136:139], v[96:111]
	v_mfma_f32_32x32x16_bf16 v[80:95], v[168:171], v[136:139], v[80:95]
	v_mfma_f32_32x32x16_bf16 v[96:111], v[206:209], v[140:143], v[96:111]
	v_mfma_f32_32x32x16_bf16 v[80:95], v[172:175], v[140:143], v[80:95]
	v_add_u32_e32 v0, v14, v196
	ds_read_b128 v[2:5], v0 offset:32768
	ds_read_b128 v[6:9], v0 offset:36864
	v_add_u32_e32 v0, v14, v197
	ds_read_b128 v[10:13], v0 offset:32768
	ds_read_b128 v[160:163], v0 offset:36864
	v_add_u32_e32 v0, v14, v198
	ds_read_b128 v[164:167], v0 offset:32768
	ds_read_b128 v[168:171], v0 offset:36864
	v_add_u32_e32 v0, v14, v199
	ds_read_b128 v[172:175], v0 offset:36864
	ds_read_b128 v[206:209], v0 offset:32768
	s_waitcnt lgkmcnt(0)
	v_mfma_f32_32x32x16_bf16 v[96:111], v[2:5], v[144:147], v[96:111]
	v_mfma_f32_32x32x16_bf16 v[80:95], v[6:9], v[144:147], v[80:95]
	v_mfma_f32_32x32x16_bf16 v[96:111], v[10:13], v[148:151], v[96:111]
	v_mfma_f32_32x32x16_bf16 v[80:95], v[160:163], v[148:151], v[80:95]
	v_mfma_f32_32x32x16_bf16 v[96:111], v[164:167], v[152:155], v[96:111]
	v_mfma_f32_32x32x16_bf16 v[80:95], v[168:171], v[152:155], v[80:95]
	v_mfma_f32_32x32x16_bf16 v[96:111], v[206:209], v[156:159], v[96:111]
	v_mfma_f32_32x32x16_bf16 v[80:95], v[172:175], v[156:159], v[80:95]
	s_nop 11
	v_max3_f32 v160, v96, v97, v98
	v_max3_f32 v161, v99, v100, v101
	v_max3_f32 v162, v102, v103, v104
	v_max3_f32 v163, v105, v106, v107
	v_max3_f32 v164, v108, v109, v110
	v_max3_f32 v165, v111, v80, v81
	v_max3_f32 v166, v82, v83, v84
	v_max3_f32 v167, v85, v86, v87
	v_max3_f32 v168, v88, v89, v90
	v_max3_f32 v169, v91, v92, v93
	v_max3_f32 v160, v160, v161, v162
	v_max3_f32 v163, v163, v164, v165
	v_max3_f32 v166, v166, v167, v168
	v_max3_f32 v169, v169, v94, v95
	v_max3_f32 v160, v160, v163, v166
	v_max_f32_e32 v160, v160, v169
	v_mov_b32_e32 v161, v160
	s_nop 1
	v_permlane32_swap_b32_e32 v160, v161
	v_max3_f32 v14, v235, v160, v161
	v_sub_f32_e32 v0, v235, v14
	v_sub_f32_e32 v96, v96, v14
	v_sub_f32_e32 v97, v97, v14
	v_sub_f32_e32 v98, v98, v14
	v_sub_f32_e32 v99, v99, v14
	v_sub_f32_e32 v100, v100, v14
	v_sub_f32_e32 v101, v101, v14
	v_sub_f32_e32 v102, v102, v14
	v_sub_f32_e32 v103, v103, v14
	v_sub_f32_e32 v104, v104, v14
	v_sub_f32_e32 v105, v105, v14
	v_sub_f32_e32 v106, v106, v14
	v_sub_f32_e32 v107, v107, v14
	v_sub_f32_e32 v108, v108, v14
	v_sub_f32_e32 v109, v109, v14
	v_sub_f32_e32 v110, v110, v14
	v_sub_f32_e32 v111, v111, v14
	v_sub_f32_e32 v80, v80, v14
	v_sub_f32_e32 v81, v81, v14
	v_sub_f32_e32 v82, v82, v14
	v_sub_f32_e32 v83, v83, v14
	v_sub_f32_e32 v84, v84, v14
	v_sub_f32_e32 v85, v85, v14
	v_sub_f32_e32 v86, v86, v14
	v_sub_f32_e32 v87, v87, v14
	v_sub_f32_e32 v88, v88, v14
	v_sub_f32_e32 v89, v89, v14
	v_sub_f32_e32 v90, v90, v14
	v_sub_f32_e32 v91, v91, v14
	v_sub_f32_e32 v92, v92, v14
	v_sub_f32_e32 v93, v93, v14
	v_sub_f32_e32 v94, v94, v14
	v_sub_f32_e32 v95, v95, v14
	v_exp_f32_e32 v0, v0
	v_exp_f32_e32 v96, v96
	v_exp_f32_e32 v97, v97
	v_exp_f32_e32 v98, v98
	v_exp_f32_e32 v99, v99
	v_exp_f32_e32 v100, v100
	v_exp_f32_e32 v101, v101
	v_exp_f32_e32 v102, v102
	v_exp_f32_e32 v103, v103
	v_exp_f32_e32 v104, v104
	v_exp_f32_e32 v105, v105
	v_exp_f32_e32 v106, v106
	v_exp_f32_e32 v107, v107
	v_exp_f32_e32 v108, v108
	v_exp_f32_e32 v109, v109
	v_exp_f32_e32 v110, v110
	v_exp_f32_e32 v111, v111
	v_exp_f32_e32 v80, v80
	v_exp_f32_e32 v81, v81
	v_exp_f32_e32 v82, v82
	v_exp_f32_e32 v83, v83
	v_exp_f32_e32 v84, v84
	v_exp_f32_e32 v85, v85
	v_exp_f32_e32 v86, v86
	v_exp_f32_e32 v87, v87
	v_exp_f32_e32 v88, v88
	v_exp_f32_e32 v89, v89
	v_exp_f32_e32 v90, v90
	v_exp_f32_e32 v91, v91
	v_exp_f32_e32 v92, v92
	v_exp_f32_e32 v93, v93
	v_exp_f32_e32 v94, v94
	v_exp_f32_e32 v95, v95
	v_pk_add_f32 v[160:161], v[96:97], v[98:99]
	v_pk_add_f32 v[162:163], v[100:101], v[102:103]
	v_pk_add_f32 v[164:165], v[104:105], v[106:107]
	v_pk_add_f32 v[166:167], v[108:109], v[110:111]
	v_pk_add_f32 v[168:169], v[80:81], v[82:83]
	v_pk_add_f32 v[170:171], v[84:85], v[86:87]
	v_pk_add_f32 v[172:173], v[88:89], v[90:91]
	v_pk_add_f32 v[174:175], v[92:93], v[94:95]
	v_pk_add_f32 v[160:161], v[160:161], v[162:163]
	v_pk_add_f32 v[164:165], v[164:165], v[166:167]
	v_pk_add_f32 v[168:169], v[168:169], v[170:171]
	v_pk_add_f32 v[172:173], v[172:173], v[174:175]
	v_pk_add_f32 v[160:161], v[160:161], v[164:165]
	v_pk_add_f32 v[168:169], v[168:169], v[172:173]
	v_pk_add_f32 v[160:161], v[160:161], v[168:169]
	v_add_f32_e32 v15, v160, v161
	v_cvt_pk_bf16_f32 v2, v80, v81
	v_cvt_pk_bf16_f32 v3, v82, v83
	v_cvt_pk_bf16_f32 v4, v84, v85
	v_cvt_pk_bf16_f32 v5, v86, v87
	v_cvt_pk_bf16_f32 v6, v88, v89
	v_cvt_pk_bf16_f32 v7, v90, v91
	v_cvt_pk_bf16_f32 v8, v92, v93
	v_cvt_pk_bf16_f32 v9, v94, v95
	v_cvt_pk_bf16_f32 v80, v104, v105
	v_cvt_pk_bf16_f32 v81, v106, v107
	v_cvt_pk_bf16_f32 v82, v108, v109
	v_cvt_pk_bf16_f32 v83, v110, v111
	v_cvt_pk_bf16_f32 v10, v96, v97
	v_cvt_pk_bf16_f32 v11, v98, v99
	v_cvt_pk_bf16_f32 v12, v100, v101
	v_cvt_pk_bf16_f32 v13, v102, v103
	v_fmac_f32_e32 v15, v234, v0
	v_cmp_neq_f32_e32 vcc, 1.0, v0
	s_cbranch_vccz .LBB0_1193
; template <bool MASKED>
; __device__ __forceinline__ void softmax_tile(f32x16& s0, f32x16& s1, float& m, float& l, float& alpha, unsigned mlo, unsigned mhi, bf16x8 (&pk)[4]) {
;     ...
;     for (int r = 0; r < 16; ++r) {
;         float p0 = __builtin_amdgcn_exp2f(s0[r] - mn), p1 = __builtin_amdgcn_exp2f(s1[r] - mn);
;         if (MASKED) { if (s0[r] <= -1e29f) p0 = 0.f; if (s1[r] <= -1e29f) p1 = 0.f; }
;         s0[r] = p0; s1[r] = p1; sum += p0 + p1;
;     }
;     l = l * alpha + sum;
	v_pk_mul_f32 v[78:79], v[78:79], v[0:1] op_sel_hi:[1,0]
	v_pk_mul_f32 v[76:77], v[76:77], v[0:1] op_sel_hi:[1,0]
	v_pk_mul_f32 v[74:75], v[74:75], v[0:1] op_sel_hi:[1,0]
	v_pk_mul_f32 v[72:73], v[72:73], v[0:1] op_sel_hi:[1,0]
	v_pk_mul_f32 v[70:71], v[70:71], v[0:1] op_sel_hi:[1,0]
	v_pk_mul_f32 v[68:69], v[68:69], v[0:1] op_sel_hi:[1,0]
	v_pk_mul_f32 v[66:67], v[66:67], v[0:1] op_sel_hi:[1,0]
	v_pk_mul_f32 v[64:65], v[64:65], v[0:1] op_sel_hi:[1,0]
	v_pk_mul_f32 v[62:63], v[62:63], v[0:1] op_sel_hi:[1,0]
	v_pk_mul_f32 v[60:61], v[60:61], v[0:1] op_sel_hi:[1,0]
	v_pk_mul_f32 v[58:59], v[58:59], v[0:1] op_sel_hi:[1,0]
	v_pk_mul_f32 v[56:57], v[56:57], v[0:1] op_sel_hi:[1,0]
	v_pk_mul_f32 v[54:55], v[54:55], v[0:1] op_sel_hi:[1,0]
	v_pk_mul_f32 v[52:53], v[52:53], v[0:1] op_sel_hi:[1,0]
	v_pk_mul_f32 v[50:51], v[50:51], v[0:1] op_sel_hi:[1,0]
	v_pk_mul_f32 v[48:49], v[48:49], v[0:1] op_sel_hi:[1,0]
	v_pk_mul_f32 v[46:47], v[46:47], v[0:1] op_sel_hi:[1,0]
	v_pk_mul_f32 v[44:45], v[44:45], v[0:1] op_sel_hi:[1,0]
	v_pk_mul_f32 v[42:43], v[42:43], v[0:1] op_sel_hi:[1,0]
	v_pk_mul_f32 v[40:41], v[40:41], v[0:1] op_sel_hi:[1,0]
	v_pk_mul_f32 v[38:39], v[38:39], v[0:1] op_sel_hi:[1,0]
	v_pk_mul_f32 v[36:37], v[36:37], v[0:1] op_sel_hi:[1,0]
	v_pk_mul_f32 v[34:35], v[34:35], v[0:1] op_sel_hi:[1,0]
	v_pk_mul_f32 v[32:33], v[32:33], v[0:1] op_sel_hi:[1,0]
	v_pk_mul_f32 v[30:31], v[30:31], v[0:1] op_sel_hi:[1,0]
	v_pk_mul_f32 v[28:29], v[28:29], v[0:1] op_sel_hi:[1,0]
	v_pk_mul_f32 v[26:27], v[26:27], v[0:1] op_sel_hi:[1,0]
	v_pk_mul_f32 v[24:25], v[24:25], v[0:1] op_sel_hi:[1,0]
	v_pk_mul_f32 v[22:23], v[22:23], v[0:1] op_sel_hi:[1,0]
	v_pk_mul_f32 v[20:21], v[20:21], v[0:1] op_sel_hi:[1,0]
	v_pk_mul_f32 v[18:19], v[18:19], v[0:1] op_sel_hi:[1,0]
	v_pk_mul_f32 v[16:17], v[16:17], v[0:1] op_sel_hi:[1,0]
.LBB0_1193:
	v_add_u32_e32 v0, s15, v187
	v_add_u32_e32 v164, v0, v218
	v_add_u32_e32 v165, v0, v220
	v_add_u32_e32 v166, v0, v222
	v_add_u32_e32 v167, v0, v223
	v_add_u32_e32 v168, v0, v224
	v_add_u32_e32 v169, v0, v225
	v_add_u32_e32 v170, v0, v226
	v_add_u32_e32 v0, v0, v227
	v_add_u32_e32 v84, v164, v219
	v_add_u32_e32 v86, v165, v221
	v_add_u32_e32 v88, v166, v219
	v_add_u32_e32 v90, v167, v221
	v_add_u32_e32 v92, v168, v219
	v_add_u32_e32 v94, v169, v221
	v_add_u32_e32 v96, v170, v219
	v_add_u32_e32 v98, v0, v221
	v_add_u32_e32 v100, v164, v228
	v_add_u32_e32 v102, v165, v229
	v_add_u32_e32 v104, v166, v228
	v_add_u32_e32 v106, v167, v229
	v_add_u32_e32 v108, v168, v228
	v_add_u32_e32 v110, v169, v229
	v_add_u32_e32 v160, v170, v228
	v_add_u32_e32 v162, v0, v229
	ds_read_b64_tr_b16 v[84:85], v84
	ds_read_b64_tr_b16 v[86:87], v86
	ds_read_b64_tr_b16 v[88:89], v88
	ds_read_b64_tr_b16 v[90:91], v90
	ds_read_b64_tr_b16 v[92:93], v92
	ds_read_b64_tr_b16 v[94:95], v94
	ds_read_b64_tr_b16 v[96:97], v96
	ds_read_b64_tr_b16 v[98:99], v98
	ds_read_b64_tr_b16 v[100:101], v100
	ds_read_b64_tr_b16 v[102:103], v102
	ds_read_b64_tr_b16 v[104:105], v104
	ds_read_b64_tr_b16 v[106:107], v106
	ds_read_b64_tr_b16 v[108:109], v108
	ds_read_b64_tr_b16 v[110:111], v110
	ds_read_b64_tr_b16 v[160:161], v160
	ds_read_b64_tr_b16 v[162:163], v162
	s_waitcnt lgkmcnt(0)
	s_nop 0
	v_mfma_f32_32x32x16_bf16 v[64:79], v[84:87], v[10:13], v[64:79]
	v_mfma_f32_32x32x16_bf16 v[48:63], v[100:103], v[10:13], v[48:63]
	v_mfma_f32_32x32x16_bf16 v[64:79], v[88:91], v[80:83], v[64:79]
	v_mfma_f32_32x32x16_bf16 v[48:63], v[104:107], v[80:83], v[48:63]
	v_mfma_f32_32x32x16_bf16 v[64:79], v[92:95], v[2:5], v[64:79]
	v_mfma_f32_32x32x16_bf16 v[48:63], v[108:111], v[2:5], v[48:63]
	v_mfma_f32_32x32x16_bf16 v[64:79], v[96:99], v[6:9], v[64:79]
	v_mfma_f32_32x32x16_bf16 v[48:63], v[160:163], v[6:9], v[48:63]
	v_add_u32_e32 v84, v164, v230
	v_add_u32_e32 v86, v165, v231
	v_add_u32_e32 v88, v166, v230
	v_add_u32_e32 v90, v167, v231
	v_add_u32_e32 v92, v168, v230
	v_add_u32_e32 v94, v169, v231
	v_add_u32_e32 v96, v170, v230
	v_add_u32_e32 v98, v0, v231
	v_add_u32_e32 v100, v164, v232
	v_add_u32_e32 v102, v165, v233
	v_add_u32_e32 v104, v166, v232
	v_add_u32_e32 v106, v167, v233
	v_add_u32_e32 v108, v168, v232
	v_add_u32_e32 v110, v169, v233
	v_add_u32_e32 v160, v170, v232
	ds_read_b64_tr_b16 v[84:85], v84
	ds_read_b64_tr_b16 v[86:87], v86
	ds_read_b64_tr_b16 v[88:89], v88
	ds_read_b64_tr_b16 v[90:91], v90
	ds_read_b64_tr_b16 v[92:93], v92
	ds_read_b64_tr_b16 v[94:95], v94
	ds_read_b64_tr_b16 v[96:97], v96
	ds_read_b64_tr_b16 v[98:99], v98
	ds_read_b64_tr_b16 v[100:101], v100
	ds_read_b64_tr_b16 v[102:103], v102
	ds_read_b64_tr_b16 v[104:105], v104
	ds_read_b64_tr_b16 v[106:107], v106
	ds_read_b64_tr_b16 v[108:109], v108
	ds_read_b64_tr_b16 v[110:111], v110
	ds_read_b64_tr_b16 v[160:161], v160
	v_add_u32_e32 v0, v0, v233
	ds_read_b64_tr_b16 v[162:163], v0
	s_waitcnt lgkmcnt(0)
	v_mfma_f32_32x32x16_bf16 v[32:47], v[84:87], v[10:13], v[32:47]
	v_mfma_f32_32x32x16_bf16 v[16:31], v[100:103], v[10:13], v[16:31]
	v_mfma_f32_32x32x16_bf16 v[32:47], v[88:91], v[80:83], v[32:47]
	v_mfma_f32_32x32x16_bf16 v[16:31], v[104:107], v[80:83], v[16:31]
	v_mfma_f32_32x32x16_bf16 v[32:47], v[92:95], v[2:5], v[32:47]
	v_mfma_f32_32x32x16_bf16 v[16:31], v[108:111], v[2:5], v[16:31]
	v_mfma_f32_32x32x16_bf16 v[32:47], v[96:99], v[6:9], v[32:47]
	v_mfma_f32_32x32x16_bf16 v[16:31], v[160:163], v[6:9], v[16:31]
	v_mov_b32_e32 v234, v15
	s_andn2_b64 vcc, exec, s[12:13]
	s_mov_b64 s[12:13], -1
	s_cbranch_vccz .LBB0_1195
	s_branch .LBB0_1196
